# S3 SSD-unit final rescale and attention-unit output stage: parameter loads hoisted (counted vmcnt)
# baseline (speedup 1.0000x reference)
; #define LAS __attribute__((address_space(3)))
; DI void attn_unit(LAS unsigned char* lds, int tid, const bf16* __restrict__ P, const bf16* __restrict__ Vt, bf16* MG, int b, int h, int qrow0, int jt0, int jt1,
;                   float lam, float oscale, const float* subg) {
;     ...
;     __syncthreads();
;     const float l = lrun + __shfl_xor(lrun, 32);
;     const float inv = (m ? lam : 1.0f) / l;
;     LAS float* X = (LAS float*)lds + qb * 4096 + lane;
;     if (m) {
; #pragma unroll
;         for (int es = 0; es < 4; ++es)
; #pragma unroll
;             for (int i = 0; i < 16; ++i) X[(es * 16 + i) * 64] = O[es][i] * inv;
;     }
;     __syncthreads();
;     if (!m) {
;         float ss = 0.f;
; #pragma unroll
;         for (int es = 0; es < 4; ++es)
; #pragma unroll
;             for (int i = 0; i < 16; ++i) { const float o = O[es][i] * inv - X[(es * 16 + i) * 64]; O[es][i] = o; ss += o * o; }
;         ss += __shfl_xor(ss, 32);
.LBB0_316:
	s_or_b64 exec, exec, s[2:3]
	s_waitcnt lgkmcnt(0)
	s_barrier
	s_and_saveexec_b64 s[2:3], s[0:1]
	s_cbranch_execz .LBB0_294
	ds_read2st64_b32 v[88:89], v82 offset1:1
	ds_read2st64_b32 v[90:91], v82 offset0:2 offset1:3
	ds_read2st64_b32 v[104:105], v82 offset0:4 offset1:5
	ds_read2st64_b32 v[96:97], v82 offset0:6 offset1:7
	ds_read2st64_b32 v[106:107], v82 offset0:8 offset1:9
	s_waitcnt vmcnt(2)
	ds_read2st64_b32 v[132:133], v82 offset0:10 offset1:11
	ds_read2st64_b32 v[128:129], v82 offset0:12 offset1:13
	ds_read2st64_b32 v[134:135], v82 offset0:14 offset1:15
	ds_read2st64_b32 v[124:125], v82 offset0:16 offset1:17
	ds_read2st64_b32 v[130:131], v82 offset0:18 offset1:19
	ds_read2st64_b32 v[120:121], v82 offset0:20 offset1:21
	ds_read2st64_b32 v[126:127], v82 offset0:22 offset1:23
	ds_read2st64_b32 v[116:117], v82 offset0:24 offset1:25
	ds_read2st64_b32 v[122:123], v82 offset0:26 offset1:27
	ds_read2st64_b32 v[112:113], v82 offset0:28 offset1:29
	ds_read2st64_b32 v[118:119], v82 offset0:30 offset1:31
	ds_read2st64_b32 v[102:103], v82 offset0:32 offset1:33
	ds_read2st64_b32 v[114:115], v82 offset0:34 offset1:35
	ds_read2st64_b32 v[98:99], v82 offset0:36 offset1:37
	ds_read2st64_b32 v[108:109], v82 offset0:38 offset1:39
	ds_read2st64_b32 v[92:93], v82 offset0:40 offset1:41
	ds_read2st64_b32 v[100:101], v82 offset0:42 offset1:43
	ds_read2st64_b32 v[86:87], v82 offset0:44 offset1:45
	ds_read2st64_b32 v[94:95], v82 offset0:46 offset1:47
	ds_read2st64_b32 v[80:81], v82 offset0:48 offset1:49
	ds_read2st64_b32 v[84:85], v82 offset0:50 offset1:51
	ds_read2st64_b32 v[76:77], v82 offset0:52 offset1:53
	ds_read2st64_b32 v[78:79], v82 offset0:54 offset1:55
	ds_read2st64_b32 v[72:73], v82 offset0:56 offset1:57
	ds_read2st64_b32 v[64:65], v82 offset0:58 offset1:59
	s_waitcnt lgkmcnt(14)
	v_pk_fma_f32 v[96:97], v[54:55], v[68:69], v[96:97] op_sel_hi:[1,0,1] neg_lo:[0,0,1] neg_hi:[0,0,1]
	v_pk_fma_f32 v[104:105], v[52:53], v[68:69], v[104:105] op_sel_hi:[1,0,1] neg_lo:[0,0,1] neg_hi:[0,0,1]
	v_pk_fma_f32 v[106:107], v[56:57], v[68:69], v[106:107] op_sel_hi:[1,0,1] neg_lo:[0,0,1] neg_hi:[0,0,1]
	v_pk_fma_f32 v[62:63], v[62:63], v[68:69], v[134:135] op_sel_hi:[1,0,1] neg_lo:[0,0,1] neg_hi:[0,0,1]
	s_waitcnt lgkmcnt(0)
	v_pk_fma_f32 v[64:65], v[10:11], v[68:69], v[64:65] op_sel_hi:[1,0,1] neg_lo:[0,0,1] neg_hi:[0,0,1]
	ds_read2st64_b32 v[10:11], v82 offset0:60 offset1:61
	v_pk_fma_f32 v[60:61], v[60:61], v[68:69], v[128:129] op_sel_hi:[1,0,1] neg_lo:[0,0,1] neg_hi:[0,0,1]
	v_pk_fma_f32 v[56:57], v[34:35], v[68:69], v[130:131] op_sel_hi:[1,0,1] neg_lo:[0,0,1] neg_hi:[0,0,1]
	v_pk_fma_f32 v[54:55], v[36:37], v[68:69], v[120:121] op_sel_hi:[1,0,1] neg_lo:[0,0,1] neg_hi:[0,0,1]
	v_pk_fma_f32 v[42:43], v[42:43], v[68:69], v[122:123] op_sel_hi:[1,0,1] neg_lo:[0,0,1] neg_hi:[0,0,1]
	s_waitcnt lgkmcnt(0)
	v_pk_fma_f32 v[66:67], v[12:13], v[68:69], v[10:11] op_sel_hi:[1,0,1] neg_lo:[0,0,1] neg_hi:[0,0,1]
	ds_read2st64_b32 v[10:11], v82 offset0:62 offset1:63
	v_pk_fma_f32 v[82:83], v[50:51], v[68:69], v[90:91] op_sel_hi:[1,0,1] neg_lo:[0,0,1] neg_hi:[0,0,1]
	v_pk_fma_f32 v[90:91], v[48:49], v[68:69], v[88:89] op_sel_hi:[1,0,1] neg_lo:[0,0,1] neg_hi:[0,0,1]
	s_waitcnt vmcnt(1)
	v_pk_mul_f32 v[138:139], v[82:83], v[82:83]
	s_waitcnt vmcnt(0)
	v_pk_mul_f32 v[140:141], v[90:91], v[90:91]
	s_waitcnt lgkmcnt(0)
	v_pk_fma_f32 v[14:15], v[14:15], v[68:69], v[10:11] op_sel_hi:[1,0,1] neg_lo:[0,0,1] neg_hi:[0,0,1]
	v_pk_fma_f32 v[88:89], v[58:59], v[68:69], v[132:133] op_sel_hi:[1,0,1] neg_lo:[0,0,1] neg_hi:[0,0,1]
	v_pk_fma_f32 v[58:59], v[32:33], v[68:69], v[124:125] op_sel_hi:[1,0,1] neg_lo:[0,0,1] neg_hi:[0,0,1]
	v_pk_fma_f32 v[50:51], v[38:39], v[68:69], v[126:127] op_sel_hi:[1,0,1] neg_lo:[0,0,1] neg_hi:[0,0,1]
	v_pk_fma_f32 v[52:53], v[40:41], v[68:69], v[116:117] op_sel_hi:[1,0,1] neg_lo:[0,0,1] neg_hi:[0,0,1]
	v_pk_fma_f32 v[40:41], v[46:47], v[68:69], v[118:119] op_sel_hi:[1,0,1] neg_lo:[0,0,1] neg_hi:[0,0,1]
	v_pk_fma_f32 v[44:45], v[44:45], v[68:69], v[112:113] op_sel_hi:[1,0,1] neg_lo:[0,0,1] neg_hi:[0,0,1]
	v_pk_fma_f32 v[36:37], v[18:19], v[68:69], v[114:115] op_sel_hi:[1,0,1] neg_lo:[0,0,1] neg_hi:[0,0,1]
	v_pk_fma_f32 v[38:39], v[16:17], v[68:69], v[102:103] op_sel_hi:[1,0,1] neg_lo:[0,0,1] neg_hi:[0,0,1]
	v_pk_fma_f32 v[32:33], v[22:23], v[68:69], v[108:109] op_sel_hi:[1,0,1] neg_lo:[0,0,1] neg_hi:[0,0,1]
	v_pk_fma_f32 v[34:35], v[20:21], v[68:69], v[98:99] op_sel_hi:[1,0,1] neg_lo:[0,0,1] neg_hi:[0,0,1]
	v_pk_fma_f32 v[22:23], v[26:27], v[68:69], v[100:101] op_sel_hi:[1,0,1] neg_lo:[0,0,1] neg_hi:[0,0,1]
	v_pk_fma_f32 v[26:27], v[24:25], v[68:69], v[92:93] op_sel_hi:[1,0,1] neg_lo:[0,0,1] neg_hi:[0,0,1]
	v_pk_fma_f32 v[20:21], v[30:31], v[68:69], v[94:95] op_sel_hi:[1,0,1] neg_lo:[0,0,1] neg_hi:[0,0,1]
	v_pk_fma_f32 v[24:25], v[28:29], v[68:69], v[86:87] op_sel_hi:[1,0,1] neg_lo:[0,0,1] neg_hi:[0,0,1]
	v_pk_fma_f32 v[16:17], v[2:3], v[68:69], v[84:85] op_sel_hi:[1,0,1] neg_lo:[0,0,1] neg_hi:[0,0,1]
	v_pk_fma_f32 v[18:19], v[0:1], v[68:69], v[80:81] op_sel_hi:[1,0,1] neg_lo:[0,0,1] neg_hi:[0,0,1]
	v_pk_fma_f32 v[2:3], v[6:7], v[68:69], v[78:79] op_sel_hi:[1,0,1] neg_lo:[0,0,1] neg_hi:[0,0,1]
	v_pk_fma_f32 v[4:5], v[4:5], v[68:69], v[76:77] op_sel_hi:[1,0,1] neg_lo:[0,0,1] neg_hi:[0,0,1]
	v_pk_fma_f32 v[0:1], v[8:9], v[68:69], v[72:73] op_sel_hi:[1,0,1] neg_lo:[0,0,1] neg_hi:[0,0,1]
	v_add_f32_e32 v68, v140, v141
	v_lshlrev_b64 v[10:11], 11, v[156:157]
	v_readlane_b32 s16, v253, 6
	v_add_f32_e32 v68, v68, v138
	v_lshl_add_u64 v[10:11], s[70:71], 0, v[10:11]
	v_readlane_b32 s17, v253, 7
	v_pk_mul_f32 v[142:143], v[104:105], v[104:105]
; DI unsigned pk2(float lo, float hi) { f32x2 v = {lo, hi}; bf16x2_t b = __builtin_convertvector(v, bf16x2_t); return __builtin_bit_cast(unsigned, b); }
; DI void attn_unit(LAS unsigned char* lds, int tid, const bf16* __restrict__ P, const bf16* __restrict__ Vt, bf16* MG, int b, int h, int qrow0, int jt0, int jt1,
;                   float lam, float oscale, const float* subg) {
;     ...
;     if (!m) {
;         float ss = 0.f;
; #pragma unroll
;         for (int es = 0; es < 4; ++es)
; #pragma unroll
;             for (int i = 0; i < 16; ++i) { const float o = O[es][i] * inv - X[(es * 16 + i) * 64]; O[es][i] = o; ss += o * o; }
;         ss += __shfl_xor(ss, 32);
;         const float rn = (1.0f / sqrtf(ss * (1.0f / 128.0f) + 1e-6f)) * oscale;
; #pragma unroll
;         for (int es = 0; es < 4; ++es)
; #pragma unroll
;             for (int g4 = 0; g4 < 4; ++g4) {
;                 const int e = es * 32 + 8 * g4 + 4 * hi;
;                 const f32x4 gv = *(const f32x4*)(subg + e);
;                 u32x2 w; w.x = pk2(O[es][4 * g4 + 0] * rn * gv.x, O[es][4 * g4 + 1] * rn * gv.y); w.y = pk2(O[es][4 * g4 + 2] * rn * gv.z, O[es][4 * g4 + 3] * rn * gv.w);
;                 *(u32x2*)(MG + (size_t)qrow * DM + h * 128 + e) = w;
;             }
;     }
	v_add_f32_e32 v68, v68, v139
	v_lshl_add_u64 v[136:137], v[10:11], 0, s[16:17]
	v_lshlrev_b32_e32 v146, 3, v167
	v_add_f32_e32 v68, v68, v142
	v_lshl_add_u64 v[48:49], v[136:137], 0, v[146:147]
	v_pk_mul_f32 v[136:137], v[96:97], v[96:97]
	v_add_f32_e32 v68, v68, v143
	v_add_f32_e32 v68, v68, v136
	v_pk_mul_f32 v[150:151], v[106:107], v[106:107]
	v_add_f32_e32 v68, v68, v137
	v_add_f32_e32 v68, v68, v150
	v_pk_mul_f32 v[132:133], v[88:89], v[88:89]
	v_add_f32_e32 v68, v68, v151
	v_add_f32_e32 v68, v68, v132
	v_pk_mul_f32 v[128:129], v[60:61], v[60:61]
	v_add_f32_e32 v68, v68, v133
	v_add_f32_e32 v68, v68, v128
	v_pk_mul_f32 v[134:135], v[62:63], v[62:63]
	v_add_f32_e32 v68, v68, v129
	v_add_f32_e32 v68, v68, v134
	v_pk_mul_f32 v[124:125], v[58:59], v[58:59]
	v_add_f32_e32 v68, v68, v135
	v_add_f32_e32 v68, v68, v124
	v_pk_mul_f32 v[130:131], v[56:57], v[56:57]
	v_add_f32_e32 v68, v68, v125
	v_add_f32_e32 v68, v68, v130
	v_readlane_b32 s4, v253, 47
	v_pk_mul_f32 v[120:121], v[54:55], v[54:55]
	v_add_f32_e32 v68, v68, v131
	v_readlane_b32 s5, v253, 48
	v_add_f32_e32 v68, v68, v120
	v_pk_mul_f32 v[126:127], v[50:51], v[50:51]
	v_add_f32_e32 v68, v68, v121
	v_add_f32_e32 v68, v68, v126
	v_pk_mul_f32 v[116:117], v[52:53], v[52:53]
	global_load_dwordx4 v[10:13], v154, s[4:5]
	v_add_f32_e32 v68, v68, v127
	v_add_f32_e32 v68, v68, v116
	v_pk_mul_f32 v[122:123], v[42:43], v[42:43]
	v_add_f32_e32 v68, v68, v117
	v_add_f32_e32 v68, v68, v122
	v_pk_mul_f32 v[112:113], v[44:45], v[44:45]
	v_add_f32_e32 v68, v68, v123
	v_add_f32_e32 v68, v68, v112
	v_pk_mul_f32 v[46:47], v[40:41], v[40:41]
	v_add_f32_e32 v68, v68, v113
	v_add_f32_e32 v46, v68, v46
	v_pk_mul_f32 v[102:103], v[38:39], v[38:39]
	v_add_f32_e32 v46, v46, v47
	v_add_f32_e32 v46, v46, v102
	v_pk_mul_f32 v[114:115], v[36:37], v[36:37]
	v_add_f32_e32 v46, v46, v103
	v_add_f32_e32 v46, v46, v114
	v_pk_mul_f32 v[98:99], v[34:35], v[34:35]
	v_add_f32_e32 v46, v46, v115
	v_add_f32_e32 v46, v46, v98
	v_pk_mul_f32 v[108:109], v[32:33], v[32:33]
	v_add_f32_e32 v46, v46, v99
	v_add_f32_e32 v46, v46, v108
	v_pk_mul_f32 v[92:93], v[26:27], v[26:27]
	v_add_f32_e32 v46, v46, v109
	v_add_f32_e32 v46, v46, v92
	v_pk_mul_f32 v[100:101], v[22:23], v[22:23]
	v_add_f32_e32 v46, v46, v93
	v_add_f32_e32 v46, v46, v100
	v_pk_mul_f32 v[28:29], v[24:25], v[24:25]
	v_add_f32_e32 v46, v46, v101
	v_add_f32_e32 v28, v46, v28
	v_pk_mul_f32 v[30:31], v[20:21], v[20:21]
	v_add_f32_e32 v28, v28, v29
	v_add_f32_e32 v28, v28, v30
	v_pk_mul_f32 v[80:81], v[18:19], v[18:19]
	v_add_f32_e32 v28, v28, v31
	v_add_f32_e32 v28, v28, v80
	v_pk_mul_f32 v[84:85], v[16:17], v[16:17]
	v_add_f32_e32 v28, v28, v81
	v_add_f32_e32 v28, v28, v84
	v_pk_mul_f32 v[76:77], v[4:5], v[4:5]
	v_add_f32_e32 v28, v28, v85
	v_add_f32_e32 v28, v28, v76
	v_pk_mul_f32 v[6:7], v[2:3], v[2:3]
	v_add_f32_e32 v28, v28, v77
	v_add_f32_e32 v6, v28, v6
	v_pk_mul_f32 v[8:9], v[0:1], v[0:1]
	v_add_f32_e32 v6, v6, v7
	v_add_f32_e32 v6, v6, v8
	v_pk_mul_f32 v[70:71], v[64:65], v[64:65]
	v_add_f32_e32 v6, v6, v9
	v_add_f32_e32 v6, v6, v70
	v_pk_mul_f32 v[74:75], v[66:67], v[66:67]
	v_add_f32_e32 v6, v6, v71
	v_add_f32_e32 v6, v6, v74
	v_pk_mul_f32 v[110:111], v[14:15], v[14:15]
	v_add_f32_e32 v6, v6, v75
	v_add_f32_e32 v6, v6, v110
	v_add_f32_e32 v6, v6, v111
	ds_bpermute_b32 v7, v69, v6
	v_readlane_b32 s18, v253, 8
	v_readlane_b32 s19, v253, 9
	v_readlane_b32 s20, v253, 10
	v_readlane_b32 s21, v253, 11
	s_waitcnt lgkmcnt(0)
	v_add_f32_e32 v6, v6, v7
	v_mov_b32_e32 v7, 0x358637bd
	v_fmamk_f32 v6, v6, 0x3c000000, v7
	v_cmp_gt_f32_e32 vcc, s65, v6
	v_mul_f32_e32 v7, 0x4f800000, v6
	v_readlane_b32 s22, v253, 12
	v_cndmask_b32_e32 v6, v6, v7, vcc
	v_sqrt_f32_e32 v7, v6
	v_readlane_b32 s23, v253, 13
	v_readlane_b32 s24, v253, 14
	v_readlane_b32 s25, v253, 15
	v_add_u32_e32 v8, -1, v7
	v_fma_f32 v9, -v8, v7, v6
	v_cmp_ge_f32_e64 s[0:1], 0, v9
	v_add_u32_e32 v9, 1, v7
	v_readlane_b32 s26, v253, 16
	v_cndmask_b32_e64 v8, v7, v8, s[0:1]
	v_fma_f32 v7, -v9, v7, v6
	v_cmp_lt_f32_e64 s[0:1], 0, v7
	v_readlane_b32 s27, v253, 17
	v_readlane_b32 s28, v253, 18
	v_cndmask_b32_e64 v7, v8, v9, s[0:1]
	v_mul_f32_e32 v8, 0x37800000, v7
	v_cndmask_b32_e32 v7, v7, v8, vcc
	v_cmp_class_f32_e32 vcc, v6, v208
	v_readlane_b32 s29, v253, 19
	v_readlane_b32 s30, v253, 20
	v_cndmask_b32_e32 v6, v7, v6, vcc
	v_div_scale_f32 v7, s[0:1], v6, v6, 1.0
	v_rcp_f32_e32 v8, v7
	v_readlane_b32 s31, v253, 21
	v_fma_f32 v9, -v7, v8, 1.0
	v_fmac_f32_e32 v8, v9, v8
	v_div_scale_f32 v9, vcc, 1.0, v6, 1.0
	v_mul_f32_e32 v28, v9, v8
	v_fma_f32 v29, -v7, v28, v9
	v_fmac_f32_e32 v28, v29, v8
	v_fma_f32 v7, -v7, v28, v9
	v_div_fmas_f32 v7, v7, v8, v28
	v_div_fixup_f32 v6, v7, v6, 1.0
	v_mul_f32_e32 v6, v166, v6
	v_pk_mul_f32 v[8:9], v[90:91], v[6:7] op_sel_hi:[1,0]
	v_pk_mul_f32 v[4:5], v[4:5], v[6:7] op_sel_hi:[1,0]
	global_load_dwordx4 v[188:191], v154, s[4:5] offset:32
	global_load_dwordx4 v[192:195], v154, s[4:5] offset:64
	global_load_dwordx4 v[196:199], v154, s[4:5] offset:96
	global_load_dwordx4 v[200:203], v154, s[4:5] offset:128
	global_load_dwordx4 v[204:207], v154, s[4:5] offset:160
	global_load_dwordx4 v[218:221], v154, s[4:5] offset:192
	global_load_dwordx4 v[222:225], v154, s[4:5] offset:224
	s_waitcnt vmcnt(7)
	v_pk_mul_f32 v[8:9], v[10:11], v[8:9]
	v_pk_mul_f32 v[10:11], v[82:83], v[6:7] op_sel_hi:[1,0]
	v_cvt_pk_bf16_f32 v8, v8, v9
	v_pk_mul_f32 v[10:11], v[12:13], v[10:11]
	v_pk_mul_f32 v[12:13], v[104:105], v[6:7] op_sel_hi:[1,0]
	v_cvt_pk_bf16_f32 v9, v10, v11
	global_store_dwordx2 v[48:49], v[8:9], off
	v_pk_mul_f32 v[2:3], v[2:3], v[6:7] op_sel_hi:[1,0]
	v_pk_mul_f32 v[0:1], v[0:1], v[6:7] op_sel_hi:[1,0]
	s_waitcnt vmcnt(7)
; DI unsigned pk2(float lo, float hi) { f32x2 v = {lo, hi}; bf16x2_t b = __builtin_convertvector(v, bf16x2_t); return __builtin_bit_cast(unsigned, b); }
; DI void attn_unit(LAS unsigned char* lds, int tid, const bf16* __restrict__ P, const bf16* __restrict__ Vt, bf16* MG, int b, int h, int qrow0, int jt0, int jt1,
;                   float lam, float oscale, const float* subg) {
;     ...
; #pragma unroll
;         for (int es = 0; es < 4; ++es)
; #pragma unroll
;             for (int g4 = 0; g4 < 4; ++g4) {
;                 const int e = es * 32 + 8 * g4 + 4 * hi;
;                 const f32x4 gv = *(const f32x4*)(subg + e);
;                 u32x2 w; w.x = pk2(O[es][4 * g4 + 0] * rn * gv.x, O[es][4 * g4 + 1] * rn * gv.y); w.y = pk2(O[es][4 * g4 + 2] * rn * gv.z, O[es][4 * g4 + 3] * rn * gv.w);
;                 *(u32x2*)(MG + (size_t)qrow * DM + h * 128 + e) = w;
;             }
;     }
	v_pk_mul_f32 v[188:189], v[188:189], v[12:13]
	v_pk_mul_f32 v[12:13], v[96:97], v[6:7] op_sel_hi:[1,0]
	v_cvt_pk_bf16_f32 v188, v188, v189
	v_pk_mul_f32 v[190:191], v[190:191], v[12:13]
	v_pk_mul_f32 v[12:13], v[106:107], v[6:7] op_sel_hi:[1,0]
	v_cvt_pk_bf16_f32 v189, v190, v191
	global_store_dwordx2 v[48:49], v[188:189], off offset:16
	s_waitcnt vmcnt(7)
	v_pk_mul_f32 v[192:193], v[192:193], v[12:13]
	v_pk_mul_f32 v[12:13], v[88:89], v[6:7] op_sel_hi:[1,0]
	v_cvt_pk_bf16_f32 v192, v192, v193
	v_pk_mul_f32 v[194:195], v[194:195], v[12:13]
	v_pk_mul_f32 v[12:13], v[60:61], v[6:7] op_sel_hi:[1,0]
	v_cvt_pk_bf16_f32 v193, v194, v195
	global_store_dwordx2 v[48:49], v[192:193], off offset:32
	s_waitcnt vmcnt(7)
	v_pk_mul_f32 v[196:197], v[196:197], v[12:13]
	v_pk_mul_f32 v[12:13], v[62:63], v[6:7] op_sel_hi:[1,0]
	v_cvt_pk_bf16_f32 v196, v196, v197
	v_pk_mul_f32 v[198:199], v[198:199], v[12:13]
	v_pk_mul_f32 v[12:13], v[58:59], v[6:7] op_sel_hi:[1,0]
	v_cvt_pk_bf16_f32 v197, v198, v199
	global_store_dwordx2 v[48:49], v[196:197], off offset:48
	s_waitcnt vmcnt(7)
	v_pk_mul_f32 v[200:201], v[200:201], v[12:13]
	v_pk_mul_f32 v[12:13], v[56:57], v[6:7] op_sel_hi:[1,0]
	v_cvt_pk_bf16_f32 v200, v200, v201
	v_pk_mul_f32 v[202:203], v[202:203], v[12:13]
	v_pk_mul_f32 v[12:13], v[54:55], v[6:7] op_sel_hi:[1,0]
	v_cvt_pk_bf16_f32 v201, v202, v203
	global_store_dwordx2 v[48:49], v[200:201], off offset:64
	s_waitcnt vmcnt(7)
	v_pk_mul_f32 v[204:205], v[12:13], v[204:205]
	v_pk_mul_f32 v[12:13], v[50:51], v[6:7] op_sel_hi:[1,0]
	v_cvt_pk_bf16_f32 v204, v204, v205
	v_pk_mul_f32 v[206:207], v[12:13], v[206:207]
	v_pk_mul_f32 v[12:13], v[52:53], v[6:7] op_sel_hi:[1,0]
	v_cvt_pk_bf16_f32 v205, v206, v207
	global_store_dwordx2 v[48:49], v[204:205], off offset:80
	s_waitcnt vmcnt(7)
	v_pk_mul_f32 v[218:219], v[12:13], v[218:219]
	v_pk_mul_f32 v[12:13], v[42:43], v[6:7] op_sel_hi:[1,0]
	v_cvt_pk_bf16_f32 v218, v218, v219
	v_pk_mul_f32 v[220:221], v[12:13], v[220:221]
	v_pk_mul_f32 v[12:13], v[44:45], v[6:7] op_sel_hi:[1,0]
	v_cvt_pk_bf16_f32 v219, v220, v221
	global_store_dwordx2 v[48:49], v[218:219], off offset:96
	s_waitcnt vmcnt(7)
	v_pk_mul_f32 v[222:223], v[12:13], v[222:223]
	v_pk_mul_f32 v[12:13], v[40:41], v[6:7] op_sel_hi:[1,0]
	v_cvt_pk_bf16_f32 v222, v222, v223
	v_pk_mul_f32 v[224:225], v[12:13], v[224:225]
	v_pk_mul_f32 v[12:13], v[38:39], v[6:7] op_sel_hi:[1,0]
	v_cvt_pk_bf16_f32 v223, v224, v225
	global_store_dwordx2 v[48:49], v[222:223], off offset:112
	global_load_dwordx4 v[8:11], v154, s[4:5] offset:256
	global_load_dwordx4 v[188:191], v154, s[4:5] offset:288
	global_load_dwordx4 v[192:195], v154, s[4:5] offset:320
	global_load_dwordx4 v[196:199], v154, s[4:5] offset:352
	global_load_dwordx4 v[200:203], v154, s[4:5] offset:384
	global_load_dwordx4 v[204:207], v154, s[4:5] offset:416
	global_load_dwordx4 v[218:221], v154, s[4:5] offset:448
	global_load_dwordx4 v[222:225], v154, s[4:5] offset:480
	s_waitcnt vmcnt(7)
	v_pk_mul_f32 v[8:9], v[12:13], v[8:9]
	v_pk_mul_f32 v[12:13], v[36:37], v[6:7] op_sel_hi:[1,0]
	v_cvt_pk_bf16_f32 v8, v8, v9
	v_pk_mul_f32 v[10:11], v[12:13], v[10:11]
	v_pk_mul_f32 v[12:13], v[34:35], v[6:7] op_sel_hi:[1,0]
	v_cvt_pk_bf16_f32 v9, v10, v11
	global_store_dwordx2 v[48:49], v[8:9], off offset:128
	s_waitcnt vmcnt(7)
	v_pk_mul_f32 v[188:189], v[12:13], v[188:189]
	v_pk_mul_f32 v[12:13], v[32:33], v[6:7] op_sel_hi:[1,0]
	v_cvt_pk_bf16_f32 v188, v188, v189
	v_pk_mul_f32 v[190:191], v[12:13], v[190:191]
	v_pk_mul_f32 v[12:13], v[26:27], v[6:7] op_sel_hi:[1,0]
	v_cvt_pk_bf16_f32 v189, v190, v191
	global_store_dwordx2 v[48:49], v[188:189], off offset:144
	s_waitcnt vmcnt(7)
	v_pk_mul_f32 v[192:193], v[12:13], v[192:193]
	v_pk_mul_f32 v[12:13], v[22:23], v[6:7] op_sel_hi:[1,0]
	v_cvt_pk_bf16_f32 v192, v192, v193
	v_pk_mul_f32 v[194:195], v[12:13], v[194:195]
	v_pk_mul_f32 v[12:13], v[24:25], v[6:7] op_sel_hi:[1,0]
	v_cvt_pk_bf16_f32 v193, v194, v195
	global_store_dwordx2 v[48:49], v[192:193], off offset:160
	s_waitcnt vmcnt(7)
	v_pk_mul_f32 v[196:197], v[12:13], v[196:197]
	v_pk_mul_f32 v[12:13], v[20:21], v[6:7] op_sel_hi:[1,0]
	v_cvt_pk_bf16_f32 v196, v196, v197
	v_pk_mul_f32 v[198:199], v[12:13], v[198:199]
	v_pk_mul_f32 v[12:13], v[18:19], v[6:7] op_sel_hi:[1,0]
	v_cvt_pk_bf16_f32 v197, v198, v199
	global_store_dwordx2 v[48:49], v[196:197], off offset:176
	s_waitcnt vmcnt(7)
	v_pk_mul_f32 v[200:201], v[12:13], v[200:201]
	v_pk_mul_f32 v[12:13], v[16:17], v[6:7] op_sel_hi:[1,0]
	v_cvt_pk_bf16_f32 v200, v200, v201
	v_pk_mul_f32 v[202:203], v[12:13], v[202:203]
	s_nop 0
	v_cvt_pk_bf16_f32 v201, v202, v203
	global_store_dwordx2 v[48:49], v[200:201], off offset:192
	s_waitcnt vmcnt(7)
	v_pk_mul_f32 v[4:5], v[4:5], v[204:205]
	v_pk_mul_f32 v[2:3], v[2:3], v[206:207]
	v_cvt_pk_bf16_f32 v4, v4, v5
	v_cvt_pk_bf16_f32 v5, v2, v3
	global_store_dwordx2 v[48:49], v[4:5], off offset:208
	s_waitcnt vmcnt(7)
	v_pk_mul_f32 v[0:1], v[0:1], v[218:219]
	v_pk_mul_f32 v[218:219], v[64:65], v[6:7] op_sel_hi:[1,0]
	v_cvt_pk_bf16_f32 v0, v0, v1
	v_pk_mul_f32 v[218:219], v[218:219], v[220:221]
	v_pk_mul_f32 v[220:221], v[66:67], v[6:7] op_sel_hi:[1,0]
	v_cvt_pk_bf16_f32 v1, v218, v219
	global_store_dwordx2 v[48:49], v[0:1], off offset:224
	s_waitcnt vmcnt(7)
	v_pk_mul_f32 v[222:223], v[220:221], v[222:223]
	v_pk_mul_f32 v[220:221], v[14:15], v[6:7] op_sel_hi:[1,0]
	v_cvt_pk_bf16_f32 v222, v222, v223
	v_pk_mul_f32 v[224:225], v[220:221], v[224:225]
	s_nop 0
	v_cvt_pk_bf16_f32 v223, v224, v225
	global_store_dwordx2 v[48:49], v[222:223], off offset:240
	v_mov_b32_e32 v0, v222
	v_mov_b32_e32 v1, v223
	v_mov_b32_e32 v2, v224
	v_mov_b32_e32 v3, v225
	v_mov_b32_e32 v4, v220
	v_mov_b32_e32 v5, v221
	v_mov_b32_e32 v8, v204
	v_mov_b32_e32 v9, v205
	v_mov_b32_e32 v10, v206
	v_mov_b32_e32 v11, v207
	s_branch .LBB0_294

; DI unsigned pk2(float lo, float hi) { f32x2 v = {lo, hi}; bf16x2_t b = __builtin_convertvector(v, bf16x2_t); return __builtin_bit_cast(unsigned, b); }
; DI void s3_ssd_unit(LAS unsigned char* lds, int tid, const ScanCtx& C, int b, int vc) {
;     ...
;     ssq += __shfl_xor(ssq, 32);
;     __syncthreads();
;     if (hi == 0) stat[tq_ * 2 + pt] = ssq;
;     __syncthreads();
;     const float rn = 1.0f / sqrtf((stat[tq_ * 2] + stat[tq_ * 2 + 1]) * (1.0f / 256.0f) + 1e-6f);
; #pragma unroll
;     for (int h = 0; h < 4; ++h)
; #pragma unroll
;         for (int g4 = 0; g4 < 4; ++g4) {
;             const int p = pt * 32 + 8 * g4 + 4 * hi;
;             const f32x4 gv = *(const f32x4*)(C.ssmg + h * 64 + p);
;             u32x2* mp = (u32x2*)(C.MG + (size_t)rowq * DM + 512 + h * 64 + p);
;             const u32x2 v = *mp;
;             u32x2 w; w.x = pk2(bflo(v.x) * rn * gv.x, bfhi(v.x) * rn * gv.y); w.y = pk2(bflo(v.y) * rn * gv.z, bfhi(v.y) * rn * gv.w);
;             *mp = w;
;         }
.LBB0_351:
	s_or_b64 exec, exec, s[0:1]
	v_add_u32_e32 v0, 0, v0
	s_waitcnt lgkmcnt(0)
	s_barrier
	ds_read_b64 v[0:1], v0 offset:8192
	s_mov_b32 s0, 0xf800000
	v_readlane_b32 s6, v254, 11
	v_readlane_b32 s70, v254, 3
	v_readlane_b32 s74, v254, 5
	s_waitcnt lgkmcnt(0)
	v_add_f32_e32 v0, v0, v1
	v_mov_b32_e32 v1, 0x358637bd
	v_fmamk_f32 v0, v0, 0x3b800000, v1
	v_cmp_gt_f32_e32 vcc, s0, v0
	v_mul_f32_e32 v1, 0x4f800000, v0
	v_readlane_b32 s28, v254, 7
	v_cndmask_b32_e32 v0, v0, v1, vcc
	v_sqrt_f32_e32 v1, v0
	v_readlane_b32 s30, v254, 9
	s_movk_i32 s72, 0x1c00
	s_movk_i32 s66, 0xffe0
	v_add_u32_e32 v2, -1, v1
	v_fma_f32 v3, -v2, v1, v0
	v_cmp_ge_f32_e64 s[0:1], 0, v3
	v_add_u32_e32 v3, 1, v1
	s_movk_i32 s73, 0x110
	v_cndmask_b32_e64 v2, v1, v2, s[0:1]
	v_fma_f32 v1, -v3, v1, v0
	v_cmp_lt_f32_e64 s[0:1], 0, v1
	s_movk_i32 s67, 0x600
	v_readlane_b32 s71, v254, 4
	v_cndmask_b32_e64 v1, v2, v3, s[0:1]
	v_mul_f32_e32 v2, 0x37800000, v1
	v_cndmask_b32_e32 v1, v1, v2, vcc
	v_cmp_class_f32_e32 vcc, v0, v208
	v_readlane_b32 s75, v254, 6
	v_readlane_b32 s29, v254, 8
	v_cndmask_b32_e32 v0, v1, v0, vcc
	v_div_scale_f32 v1, s[0:1], v0, v0, 1.0
	v_rcp_f32_e32 v2, v1
	v_readlane_b32 s0, v254, 0
	v_readlane_b32 s1, v254, 1
	v_readlane_b32 s31, v254, 10
	v_fma_f32 v3, -v1, v2, 1.0
	v_fmac_f32_e32 v2, v3, v2
	v_div_scale_f32 v3, vcc, 1.0, v0, 1.0
	v_mul_f32_e32 v4, v3, v2
	v_fma_f32 v5, -v1, v4, v3
	v_fmac_f32_e32 v4, v5, v2
	v_fma_f32 v1, -v1, v4, v3
	v_div_fmas_f32 v1, v1, v2, v4
	v_div_fixup_f32 v0, v1, v0, 1.0
	v_lshlrev_b32_e32 v1, 2, v94
	global_load_dwordx4 v[2:5], v1, s[0:1]
	global_load_dwordx2 v[6:7], v[80:81], off offset:1024
	global_load_dwordx4 v[96:99], v1, s[0:1] offset:32
	global_load_dwordx2 v[100:101], v[80:81], off offset:1040
	global_load_dwordx4 v[102:105], v1, s[0:1] offset:64
	global_load_dwordx2 v[106:107], v[80:81], off offset:1056
	global_load_dwordx4 v[108:111], v1, s[0:1] offset:96
	global_load_dwordx2 v[112:113], v[80:81], off offset:1072
	global_load_dwordx4 v[114:117], v1, s[0:1] offset:256
	global_load_dwordx2 v[118:119], v[80:81], off offset:1152
	global_load_dwordx4 v[120:123], v1, s[0:1] offset:288
	global_load_dwordx2 v[124:125], v[80:81], off offset:1168
	global_load_dwordx4 v[126:129], v1, s[0:1] offset:320
	global_load_dwordx2 v[130:131], v[80:81], off offset:1184
	global_load_dwordx4 v[132:135], v1, s[0:1] offset:352
	global_load_dwordx2 v[136:137], v[80:81], off offset:1200
	global_load_dwordx4 v[138:141], v1, s[0:1] offset:512
	global_load_dwordx2 v[142:143], v[80:81], off offset:1280
	global_load_dwordx4 v[160:163], v1, s[0:1] offset:544
	global_load_dwordx2 v[164:165], v[80:81], off offset:1296
	global_load_dwordx4 v[168:171], v1, s[0:1] offset:576
	global_load_dwordx2 v[172:173], v[80:81], off offset:1312
	global_load_dwordx4 v[174:177], v1, s[0:1] offset:608
	global_load_dwordx2 v[178:179], v[80:81], off offset:1328
	global_load_dwordx4 v[180:183], v1, s[0:1] offset:768
	global_load_dwordx2 v[184:185], v[80:81], off offset:1408
	global_load_dwordx4 v[186:189], v1, s[0:1] offset:800
	global_load_dwordx2 v[190:191], v[80:81], off offset:1424
	global_load_dwordx4 v[192:195], v1, s[0:1] offset:832
	global_load_dwordx2 v[196:197], v[80:81], off offset:1440
	global_load_dwordx4 v[198:201], v1, s[0:1] offset:864
	global_load_dwordx2 v[202:203], v[80:81], off offset:1456
	s_waitcnt vmcnt(30)
	v_lshlrev_b32_e32 v8, 16, v6
	v_and_b32_e32 v9, 0xffff0000, v6
	v_lshlrev_b32_e32 v6, 16, v7
	v_and_b32_e32 v7, 0xffff0000, v7
	v_pk_mul_f32 v[8:9], v[0:1], v[8:9] op_sel_hi:[0,1]
	v_pk_mul_f32 v[6:7], v[0:1], v[6:7] op_sel_hi:[0,1]
	v_pk_mul_f32 v[2:3], v[2:3], v[8:9]
	v_pk_mul_f32 v[4:5], v[4:5], v[6:7]
	v_cvt_pk_bf16_f32 v2, v2, v3
	v_cvt_pk_bf16_f32 v3, v4, v5
	global_store_dwordx2 v[80:81], v[2:3], off offset:1024
	s_nop 0
	s_waitcnt vmcnt(29)
	v_lshlrev_b32_e32 v8, 16, v100
	v_and_b32_e32 v9, 0xffff0000, v100
	v_lshlrev_b32_e32 v100, 16, v101
	v_and_b32_e32 v101, 0xffff0000, v101
	v_pk_mul_f32 v[8:9], v[0:1], v[8:9] op_sel_hi:[0,1]
	v_pk_mul_f32 v[100:101], v[0:1], v[100:101] op_sel_hi:[0,1]
	v_pk_mul_f32 v[96:97], v[96:97], v[8:9]
	v_pk_mul_f32 v[98:99], v[98:99], v[100:101]
	v_cvt_pk_bf16_f32 v96, v96, v97
	v_cvt_pk_bf16_f32 v97, v98, v99
	global_store_dwordx2 v[80:81], v[96:97], off offset:1040
	s_nop 0
	s_waitcnt vmcnt(28)
	v_lshlrev_b32_e32 v8, 16, v106
	v_and_b32_e32 v9, 0xffff0000, v106
	v_lshlrev_b32_e32 v106, 16, v107
	v_and_b32_e32 v107, 0xffff0000, v107
	v_pk_mul_f32 v[8:9], v[0:1], v[8:9] op_sel_hi:[0,1]
	v_pk_mul_f32 v[106:107], v[0:1], v[106:107] op_sel_hi:[0,1]
	v_pk_mul_f32 v[102:103], v[102:103], v[8:9]
	v_pk_mul_f32 v[104:105], v[104:105], v[106:107]
	v_cvt_pk_bf16_f32 v102, v102, v103
	v_cvt_pk_bf16_f32 v103, v104, v105
	global_store_dwordx2 v[80:81], v[102:103], off offset:1056
	s_nop 0
	s_waitcnt vmcnt(27)
	v_lshlrev_b32_e32 v8, 16, v112
	v_and_b32_e32 v9, 0xffff0000, v112
	v_lshlrev_b32_e32 v112, 16, v113
	v_and_b32_e32 v113, 0xffff0000, v113
	v_pk_mul_f32 v[8:9], v[0:1], v[8:9] op_sel_hi:[0,1]
	v_pk_mul_f32 v[112:113], v[0:1], v[112:113] op_sel_hi:[0,1]
	v_pk_mul_f32 v[108:109], v[108:109], v[8:9]
	v_pk_mul_f32 v[110:111], v[110:111], v[112:113]
	v_cvt_pk_bf16_f32 v108, v108, v109
	v_cvt_pk_bf16_f32 v109, v110, v111
	global_store_dwordx2 v[80:81], v[108:109], off offset:1072
	s_nop 0
	s_waitcnt vmcnt(26)
	v_lshlrev_b32_e32 v8, 16, v118
	v_and_b32_e32 v9, 0xffff0000, v118
	v_lshlrev_b32_e32 v118, 16, v119
	v_and_b32_e32 v119, 0xffff0000, v119
	v_pk_mul_f32 v[8:9], v[0:1], v[8:9] op_sel_hi:[0,1]
	v_pk_mul_f32 v[118:119], v[0:1], v[118:119] op_sel_hi:[0,1]
	v_pk_mul_f32 v[114:115], v[114:115], v[8:9]
	v_pk_mul_f32 v[116:117], v[116:117], v[118:119]
	v_cvt_pk_bf16_f32 v114, v114, v115
	v_cvt_pk_bf16_f32 v115, v116, v117
	global_store_dwordx2 v[80:81], v[114:115], off offset:1152
	s_nop 0
	s_waitcnt vmcnt(25)
; DI unsigned pk2(float lo, float hi) { f32x2 v = {lo, hi}; bf16x2_t b = __builtin_convertvector(v, bf16x2_t); return __builtin_bit_cast(unsigned, b); }
; DI void s3_ssd_unit(LAS unsigned char* lds, int tid, const ScanCtx& C, int b, int vc) {
;     ...
;     const float rn = 1.0f / sqrtf((stat[tq_ * 2] + stat[tq_ * 2 + 1]) * (1.0f / 256.0f) + 1e-6f);
; #pragma unroll
;     for (int h = 0; h < 4; ++h)
; #pragma unroll
;         for (int g4 = 0; g4 < 4; ++g4) {
;             const int p = pt * 32 + 8 * g4 + 4 * hi;
;             const f32x4 gv = *(const f32x4*)(C.ssmg + h * 64 + p);
;             u32x2* mp = (u32x2*)(C.MG + (size_t)rowq * DM + 512 + h * 64 + p);
;             const u32x2 v = *mp;
;             u32x2 w; w.x = pk2(bflo(v.x) * rn * gv.x, bfhi(v.x) * rn * gv.y); w.y = pk2(bflo(v.y) * rn * gv.z, bfhi(v.y) * rn * gv.w);
;             *mp = w;
;         }
	v_lshlrev_b32_e32 v8, 16, v124
	v_and_b32_e32 v9, 0xffff0000, v124
	v_lshlrev_b32_e32 v124, 16, v125
	v_and_b32_e32 v125, 0xffff0000, v125
	v_pk_mul_f32 v[8:9], v[0:1], v[8:9] op_sel_hi:[0,1]
	v_pk_mul_f32 v[124:125], v[0:1], v[124:125] op_sel_hi:[0,1]
	v_pk_mul_f32 v[120:121], v[120:121], v[8:9]
	v_pk_mul_f32 v[122:123], v[122:123], v[124:125]
	v_cvt_pk_bf16_f32 v120, v120, v121
	v_cvt_pk_bf16_f32 v121, v122, v123
	global_store_dwordx2 v[80:81], v[120:121], off offset:1168
	s_nop 0
	s_waitcnt vmcnt(24)
	v_lshlrev_b32_e32 v8, 16, v130
	v_and_b32_e32 v9, 0xffff0000, v130
	v_lshlrev_b32_e32 v130, 16, v131
	v_and_b32_e32 v131, 0xffff0000, v131
	v_pk_mul_f32 v[8:9], v[0:1], v[8:9] op_sel_hi:[0,1]
	v_pk_mul_f32 v[130:131], v[0:1], v[130:131] op_sel_hi:[0,1]
	v_pk_mul_f32 v[126:127], v[126:127], v[8:9]
	v_pk_mul_f32 v[128:129], v[128:129], v[130:131]
	v_cvt_pk_bf16_f32 v126, v126, v127
	v_cvt_pk_bf16_f32 v127, v128, v129
	global_store_dwordx2 v[80:81], v[126:127], off offset:1184
	s_nop 0
	s_waitcnt vmcnt(23)
	v_lshlrev_b32_e32 v8, 16, v136
	v_and_b32_e32 v9, 0xffff0000, v136
	v_lshlrev_b32_e32 v136, 16, v137
	v_and_b32_e32 v137, 0xffff0000, v137
	v_pk_mul_f32 v[8:9], v[0:1], v[8:9] op_sel_hi:[0,1]
	v_pk_mul_f32 v[136:137], v[0:1], v[136:137] op_sel_hi:[0,1]
	v_pk_mul_f32 v[132:133], v[132:133], v[8:9]
	v_pk_mul_f32 v[134:135], v[134:135], v[136:137]
	v_cvt_pk_bf16_f32 v132, v132, v133
	v_cvt_pk_bf16_f32 v133, v134, v135
	global_store_dwordx2 v[80:81], v[132:133], off offset:1200
	s_nop 0
	s_waitcnt vmcnt(22)
	v_lshlrev_b32_e32 v8, 16, v142
	v_and_b32_e32 v9, 0xffff0000, v142
	v_lshlrev_b32_e32 v142, 16, v143
	v_and_b32_e32 v143, 0xffff0000, v143
	v_pk_mul_f32 v[8:9], v[0:1], v[8:9] op_sel_hi:[0,1]
	v_pk_mul_f32 v[142:143], v[0:1], v[142:143] op_sel_hi:[0,1]
	v_pk_mul_f32 v[138:139], v[138:139], v[8:9]
	v_pk_mul_f32 v[140:141], v[140:141], v[142:143]
	v_cvt_pk_bf16_f32 v138, v138, v139
	v_cvt_pk_bf16_f32 v139, v140, v141
	global_store_dwordx2 v[80:81], v[138:139], off offset:1280
	s_nop 0
	s_waitcnt vmcnt(21)
	v_lshlrev_b32_e32 v8, 16, v164
	v_and_b32_e32 v9, 0xffff0000, v164
	v_lshlrev_b32_e32 v164, 16, v165
	v_and_b32_e32 v165, 0xffff0000, v165
	v_pk_mul_f32 v[8:9], v[0:1], v[8:9] op_sel_hi:[0,1]
	v_pk_mul_f32 v[164:165], v[0:1], v[164:165] op_sel_hi:[0,1]
	v_pk_mul_f32 v[160:161], v[160:161], v[8:9]
	v_pk_mul_f32 v[162:163], v[162:163], v[164:165]
	v_cvt_pk_bf16_f32 v160, v160, v161
	v_cvt_pk_bf16_f32 v161, v162, v163
	global_store_dwordx2 v[80:81], v[160:161], off offset:1296
	s_nop 0
	s_waitcnt vmcnt(20)
	v_lshlrev_b32_e32 v8, 16, v172
	v_and_b32_e32 v9, 0xffff0000, v172
	v_lshlrev_b32_e32 v172, 16, v173
	v_and_b32_e32 v173, 0xffff0000, v173
	v_pk_mul_f32 v[8:9], v[0:1], v[8:9] op_sel_hi:[0,1]
	v_pk_mul_f32 v[172:173], v[0:1], v[172:173] op_sel_hi:[0,1]
	v_pk_mul_f32 v[168:169], v[168:169], v[8:9]
	v_pk_mul_f32 v[170:171], v[170:171], v[172:173]
	v_cvt_pk_bf16_f32 v168, v168, v169
	v_cvt_pk_bf16_f32 v169, v170, v171
	global_store_dwordx2 v[80:81], v[168:169], off offset:1312
	s_nop 0
	s_waitcnt vmcnt(19)
	v_lshlrev_b32_e32 v8, 16, v178
	v_and_b32_e32 v9, 0xffff0000, v178
	v_lshlrev_b32_e32 v178, 16, v179
	v_and_b32_e32 v179, 0xffff0000, v179
	v_pk_mul_f32 v[8:9], v[0:1], v[8:9] op_sel_hi:[0,1]
	v_pk_mul_f32 v[178:179], v[0:1], v[178:179] op_sel_hi:[0,1]
	v_pk_mul_f32 v[174:175], v[174:175], v[8:9]
	v_pk_mul_f32 v[176:177], v[176:177], v[178:179]
	v_cvt_pk_bf16_f32 v174, v174, v175
	v_cvt_pk_bf16_f32 v175, v176, v177
	global_store_dwordx2 v[80:81], v[174:175], off offset:1328
	s_nop 0
	s_waitcnt vmcnt(18)
	v_lshlrev_b32_e32 v8, 16, v184
	v_and_b32_e32 v9, 0xffff0000, v184
	v_lshlrev_b32_e32 v184, 16, v185
	v_and_b32_e32 v185, 0xffff0000, v185
	v_pk_mul_f32 v[8:9], v[0:1], v[8:9] op_sel_hi:[0,1]
	v_pk_mul_f32 v[184:185], v[0:1], v[184:185] op_sel_hi:[0,1]
	v_pk_mul_f32 v[180:181], v[180:181], v[8:9]
	v_pk_mul_f32 v[182:183], v[182:183], v[184:185]
	v_cvt_pk_bf16_f32 v180, v180, v181
	v_cvt_pk_bf16_f32 v181, v182, v183
	global_store_dwordx2 v[80:81], v[180:181], off offset:1408
	s_nop 0
	s_waitcnt vmcnt(17)
	v_lshlrev_b32_e32 v8, 16, v190
	v_and_b32_e32 v9, 0xffff0000, v190
	v_lshlrev_b32_e32 v190, 16, v191
	v_and_b32_e32 v191, 0xffff0000, v191
	v_pk_mul_f32 v[8:9], v[0:1], v[8:9] op_sel_hi:[0,1]
	v_pk_mul_f32 v[190:191], v[0:1], v[190:191] op_sel_hi:[0,1]
	v_pk_mul_f32 v[186:187], v[186:187], v[8:9]
	v_pk_mul_f32 v[188:189], v[188:189], v[190:191]
	v_cvt_pk_bf16_f32 v186, v186, v187
	v_cvt_pk_bf16_f32 v187, v188, v189
	global_store_dwordx2 v[80:81], v[186:187], off offset:1424
	s_nop 0
	s_waitcnt vmcnt(16)
	v_lshlrev_b32_e32 v8, 16, v196
	v_and_b32_e32 v9, 0xffff0000, v196
	v_lshlrev_b32_e32 v196, 16, v197
	v_and_b32_e32 v197, 0xffff0000, v197
	v_pk_mul_f32 v[8:9], v[0:1], v[8:9] op_sel_hi:[0,1]
	v_pk_mul_f32 v[196:197], v[0:1], v[196:197] op_sel_hi:[0,1]
	v_pk_mul_f32 v[192:193], v[192:193], v[8:9]
	v_pk_mul_f32 v[194:195], v[194:195], v[196:197]
	v_cvt_pk_bf16_f32 v192, v192, v193
	v_cvt_pk_bf16_f32 v193, v194, v195
	global_store_dwordx2 v[80:81], v[192:193], off offset:1440
	s_nop 0
	v_readlane_b32 s0, v253, 34
	s_add_i32 s6, s6, s0
	v_readlane_b32 s0, v253, 63
	s_cmp_ge_i32 s6, s0
	s_waitcnt vmcnt(15)
	v_lshlrev_b32_e32 v8, 16, v202
	v_and_b32_e32 v9, 0xffff0000, v202
	v_lshlrev_b32_e32 v202, 16, v203
	v_and_b32_e32 v203, 0xffff0000, v203
	v_pk_mul_f32 v[8:9], v[0:1], v[8:9] op_sel_hi:[0,1]
	v_pk_mul_f32 v[0:1], v[0:1], v[202:203] op_sel_hi:[0,1]
	v_pk_mul_f32 v[198:199], v[198:199], v[8:9]
	v_pk_mul_f32 v[0:1], v[200:201], v[0:1]
	v_cvt_pk_bf16_f32 v198, v198, v199
	v_cvt_pk_bf16_f32 v199, v0, v1
	global_store_dwordx2 v[80:81], v[198:199], off offset:1456
	v_mov_b32_e32 v2, v198
	v_mov_b32_e32 v3, v199
	v_mov_b32_e32 v4, v200
	v_mov_b32_e32 v5, v201
	v_mov_b32_e32 v6, v202
	v_mov_b32_e32 v7, v203
	s_cbranch_scc1 .LBB0_620
